# ffn_in ACT stores write-through (sc1) and the XCD leader skips its L2 writeback at the barrier after ffn_in
# speedup vs baseline: 1.0707x; 1.0013x over previous
.Lpf_skip:
	v_mul_f32_e32 v128, 0xbfb8aa3b, v120
	v_mul_f32_e32 v129, 0xbfb8aa3b, v121
	v_exp_f32_e32 v128, v128
	v_exp_f32_e32 v129, v129
	s_lshl_b32 s4, s4, 7
	s_movk_i32 s29, 0x1600
	s_ashr_i32 s5, s4, 31
	v_pk_add_f32 v[128:129], v[128:129], 1.0 op_sel_hi:[1,0]
	s_lshl_b64 s[4:5], s[4:5], 1
	s_lshl_b32 s84, s28, 1
	v_rcp_f32_e32 v130, v129
	s_nop 0
	v_mul_f32_e32 v121, v121, v130
	v_rcp_f32_e32 v129, v128
	s_nop 0
	v_mul_f32_e32 v120, v120, v129
	v_pk_mul_f32 v[120:121], v[120:121], v[124:125]
	v_mul_f32_e32 v124, 0xbfb8aa3b, v122
	v_mul_f32_e32 v125, 0xbfb8aa3b, v123
	v_exp_f32_e32 v124, v124
	v_exp_f32_e32 v125, v125
	v_cvt_pk_bf16_f32 v120, v120, v121
	v_pk_add_f32 v[124:125], v[124:125], 1.0 op_sel_hi:[1,0]
	s_nop 0
	v_rcp_f32_e32 v128, v125
	s_nop 0
	v_mul_f32_e32 v123, v123, v128
	v_rcp_f32_e32 v125, v124
	s_nop 0
	v_mul_f32_e32 v122, v122, v125
	v_pk_mul_f32 v[122:123], v[122:123], v[126:127]
	s_nop 0
	v_cvt_pk_bf16_f32 v121, v122, v123
	v_mul_f32_e32 v122, 0xbfb8aa3b, v112
	v_mul_f32_e32 v123, 0xbfb8aa3b, v113
	v_exp_f32_e32 v122, v122
	v_exp_f32_e32 v123, v123
	s_nop 0
	v_pk_add_f32 v[122:123], v[122:123], 1.0 op_sel_hi:[1,0]
	s_nop 0
	v_rcp_f32_e32 v124, v123
	s_nop 0
	v_mul_f32_e32 v113, v113, v124
	v_rcp_f32_e32 v123, v122
	s_nop 0
	v_mul_f32_e32 v112, v112, v123
	v_pk_mul_f32 v[112:113], v[112:113], v[116:117]
	v_mul_f32_e32 v116, 0xbfb8aa3b, v114
	v_mul_f32_e32 v117, 0xbfb8aa3b, v115
	v_exp_f32_e32 v116, v116
	v_exp_f32_e32 v117, v117
	s_nop 0
	v_pk_add_f32 v[116:117], v[116:117], 1.0 op_sel_hi:[1,0]
	s_nop 0
	v_rcp_f32_e32 v122, v117
	s_nop 0
	v_mul_f32_e32 v115, v115, v122
	v_rcp_f32_e32 v117, v116
	s_nop 0
	v_mul_f32_e32 v114, v114, v117
	v_pk_mul_f32 v[114:115], v[114:115], v[118:119]
	v_cvt_pk_bf16_f32 v122, v112, v113
	v_cvt_pk_bf16_f32 v123, v114, v115
	v_lshl_add_u32 v114, s33, 8, v140
	v_mov_b64_e32 v[112:113], s[0:1]
	v_mad_i64_i32 v[116:117], s[24:25], v114, s29, v[112:113]
	v_lshl_add_u64 v[116:117], v[116:117], 0, s[4:5]
	v_lshl_add_u64 v[116:117], v[116:117], 0, s[84:85]
	v_lshl_add_u64 v[116:117], v[116:117], 0, v[144:145]
	v_mul_f32_e32 v115, 0xbfb8aa3b, v104
	global_store_dwordx4 v[116:117], v[120:123], off sc1
	v_exp_f32_e32 v116, v115
	v_mul_f32_e32 v115, 0xbfb8aa3b, v105
	v_exp_f32_e32 v117, v115
	s_nop 0
	v_pk_add_f32 v[116:117], v[116:117], 1.0 op_sel_hi:[1,0]
	s_nop 0
	v_rcp_f32_e32 v115, v117
	s_nop 0
	v_mul_f32_e32 v105, v105, v115
	v_rcp_f32_e32 v115, v116
	s_nop 0
	v_mul_f32_e32 v104, v104, v115
	v_pk_mul_f32 v[104:105], v[104:105], v[108:109]
	v_mul_f32_e32 v108, 0xbfb8aa3b, v106
	v_mul_f32_e32 v109, 0xbfb8aa3b, v107
	v_exp_f32_e32 v108, v108
	v_exp_f32_e32 v109, v109
	v_cvt_pk_bf16_f32 v104, v104, v105
	v_pk_add_f32 v[108:109], v[108:109], 1.0 op_sel_hi:[1,0]
	s_nop 0
	v_rcp_f32_e32 v115, v109
	s_nop 0
	v_mul_f32_e32 v107, v107, v115
	v_rcp_f32_e32 v109, v108
	s_nop 0
	v_mul_f32_e32 v106, v106, v109
	v_pk_mul_f32 v[106:107], v[106:107], v[110:111]
	s_nop 0
	v_cvt_pk_bf16_f32 v105, v106, v107
	v_mul_f32_e32 v106, 0xbfb8aa3b, v96
	v_mul_f32_e32 v107, 0xbfb8aa3b, v97
	v_exp_f32_e32 v106, v106
	v_exp_f32_e32 v107, v107
	s_nop 0
	v_pk_add_f32 v[106:107], v[106:107], 1.0 op_sel_hi:[1,0]
	s_nop 0
	v_rcp_f32_e32 v108, v107
	s_nop 0
	v_mul_f32_e32 v97, v97, v108
	v_rcp_f32_e32 v107, v106
	s_nop 0
	v_mul_f32_e32 v96, v96, v107
	v_pk_mul_f32 v[96:97], v[96:97], v[100:101]
	v_mul_f32_e32 v100, 0xbfb8aa3b, v98
	v_mul_f32_e32 v101, 0xbfb8aa3b, v99
	v_exp_f32_e32 v100, v100
	v_exp_f32_e32 v101, v101
	s_nop 0
	v_pk_add_f32 v[100:101], v[100:101], 1.0 op_sel_hi:[1,0]
	s_nop 0
	v_rcp_f32_e32 v106, v101
	s_nop 0
	v_mul_f32_e32 v99, v99, v106
	v_cvt_pk_bf16_f32 v106, v96, v97
	v_add_u32_e32 v96, 16, v114
	v_mad_i64_i32 v[96:97], s[24:25], v96, s29, v[112:113]
	v_rcp_f32_e32 v101, v100
	s_nop 0
	v_mul_f32_e32 v98, v98, v101
	v_lshl_add_u64 v[96:97], v[96:97], 0, s[4:5]
	v_pk_mul_f32 v[98:99], v[98:99], v[102:103]
	v_lshl_add_u64 v[96:97], v[96:97], 0, s[84:85]
	v_cvt_pk_bf16_f32 v107, v98, v99
	v_lshl_add_u64 v[96:97], v[96:97], 0, v[144:145]
	global_store_dwordx4 v[96:97], v[104:107], off sc1
	v_mul_f32_e32 v96, 0xbfb8aa3b, v88
	v_mul_f32_e32 v97, 0xbfb8aa3b, v89
	v_exp_f32_e32 v96, v96
	v_exp_f32_e32 v97, v97
	s_nop 0
	v_pk_add_f32 v[96:97], v[96:97], 1.0 op_sel_hi:[1,0]
	s_nop 0
	v_rcp_f32_e32 v98, v97
	s_nop 0
	v_mul_f32_e32 v89, v89, v98
	v_rcp_f32_e32 v97, v96
	s_nop 0
	v_mul_f32_e32 v88, v88, v97
	v_pk_mul_f32 v[88:89], v[88:89], v[92:93]
	v_mul_f32_e32 v92, 0xbfb8aa3b, v90
	v_mul_f32_e32 v93, 0xbfb8aa3b, v91
	v_exp_f32_e32 v92, v92
	v_exp_f32_e32 v93, v93
	v_cvt_pk_bf16_f32 v88, v88, v89
	v_pk_add_f32 v[92:93], v[92:93], 1.0 op_sel_hi:[1,0]
	s_nop 0
	v_rcp_f32_e32 v96, v93
	s_nop 0
	v_mul_f32_e32 v91, v91, v96
	v_rcp_f32_e32 v93, v92
	s_nop 0
	v_mul_f32_e32 v90, v90, v93
	v_pk_mul_f32 v[90:91], v[90:91], v[94:95]
	s_nop 0
	v_cvt_pk_bf16_f32 v89, v90, v91
	v_mul_f32_e32 v90, 0xbfb8aa3b, v80
	v_mul_f32_e32 v91, 0xbfb8aa3b, v81
	v_exp_f32_e32 v90, v90
	v_exp_f32_e32 v91, v91
	s_nop 0
	v_pk_add_f32 v[90:91], v[90:91], 1.0 op_sel_hi:[1,0]
	s_nop 0
	v_rcp_f32_e32 v92, v91
	s_nop 0
	v_mul_f32_e32 v81, v81, v92
	v_rcp_f32_e32 v91, v90
	s_nop 0
	v_mul_f32_e32 v80, v80, v91
	v_pk_mul_f32 v[80:81], v[80:81], v[84:85]
	v_mul_f32_e32 v84, 0xbfb8aa3b, v82
	v_mul_f32_e32 v85, 0xbfb8aa3b, v83
	v_exp_f32_e32 v84, v84
	v_exp_f32_e32 v85, v85
	s_nop 0
	v_pk_add_f32 v[84:85], v[84:85], 1.0 op_sel_hi:[1,0]
	s_nop 0
	v_rcp_f32_e32 v90, v85
	s_nop 0
	v_mul_f32_e32 v83, v83, v90
	v_cvt_pk_bf16_f32 v90, v80, v81
	v_add_u32_e32 v80, 32, v114
	v_mad_i64_i32 v[80:81], s[24:25], v80, s29, v[112:113]
	v_rcp_f32_e32 v85, v84
	s_nop 0
	v_mul_f32_e32 v82, v82, v85
	v_lshl_add_u64 v[80:81], v[80:81], 0, s[4:5]
	v_pk_mul_f32 v[82:83], v[82:83], v[86:87]
	v_lshl_add_u64 v[80:81], v[80:81], 0, s[84:85]
	v_cvt_pk_bf16_f32 v91, v82, v83
	v_lshl_add_u64 v[80:81], v[80:81], 0, v[144:145]
	global_store_dwordx4 v[80:81], v[88:91], off sc1
	v_mul_f32_e32 v80, 0xbfb8aa3b, v72
	v_mul_f32_e32 v81, 0xbfb8aa3b, v73
	v_exp_f32_e32 v80, v80
	v_exp_f32_e32 v81, v81
	s_nop 0
	v_pk_add_f32 v[80:81], v[80:81], 1.0 op_sel_hi:[1,0]
	s_nop 0
	v_rcp_f32_e32 v82, v81
	s_nop 0
	v_mul_f32_e32 v73, v73, v82
	v_rcp_f32_e32 v81, v80
	s_nop 0
	v_mul_f32_e32 v72, v72, v81
	v_pk_mul_f32 v[72:73], v[72:73], v[76:77]
	v_mul_f32_e32 v76, 0xbfb8aa3b, v74
	v_mul_f32_e32 v77, 0xbfb8aa3b, v75
	v_exp_f32_e32 v76, v76
	v_exp_f32_e32 v77, v77
	v_cvt_pk_bf16_f32 v72, v72, v73
	v_pk_add_f32 v[76:77], v[76:77], 1.0 op_sel_hi:[1,0]
	s_nop 0
	v_rcp_f32_e32 v80, v77
	s_nop 0
	v_mul_f32_e32 v75, v75, v80
	v_rcp_f32_e32 v77, v76
	s_nop 0
	v_mul_f32_e32 v74, v74, v77
	v_pk_mul_f32 v[74:75], v[74:75], v[78:79]
	s_nop 0
	v_cvt_pk_bf16_f32 v73, v74, v75
	v_mul_f32_e32 v74, 0xbfb8aa3b, v64
	v_mul_f32_e32 v75, 0xbfb8aa3b, v65
	v_exp_f32_e32 v74, v74
	v_exp_f32_e32 v75, v75
	s_nop 0
	v_pk_add_f32 v[74:75], v[74:75], 1.0 op_sel_hi:[1,0]
	s_nop 0
	v_rcp_f32_e32 v76, v75
	s_nop 0
	v_mul_f32_e32 v65, v65, v76
	v_rcp_f32_e32 v75, v74
	s_nop 0
	v_mul_f32_e32 v64, v64, v75
	v_pk_mul_f32 v[64:65], v[64:65], v[68:69]
	v_mul_f32_e32 v68, 0xbfb8aa3b, v66
	v_mul_f32_e32 v69, 0xbfb8aa3b, v67
	v_exp_f32_e32 v68, v68
	v_exp_f32_e32 v69, v69
	s_nop 0
	v_pk_add_f32 v[68:69], v[68:69], 1.0 op_sel_hi:[1,0]
	s_nop 0
	v_rcp_f32_e32 v74, v69
	s_nop 0
	v_mul_f32_e32 v67, v67, v74
	v_cvt_pk_bf16_f32 v74, v64, v65
	v_add_u32_e32 v64, 48, v114
	v_mad_i64_i32 v[64:65], s[24:25], v64, s29, v[112:113]
	v_rcp_f32_e32 v69, v68
	s_nop 0
	v_mul_f32_e32 v66, v66, v69
	v_lshl_add_u64 v[64:65], v[64:65], 0, s[4:5]
	v_pk_mul_f32 v[66:67], v[66:67], v[70:71]
	v_lshl_add_u64 v[64:65], v[64:65], 0, s[84:85]
	v_cvt_pk_bf16_f32 v75, v66, v67
	v_lshl_add_u64 v[64:65], v[64:65], 0, v[144:145]
	global_store_dwordx4 v[64:65], v[72:75], off sc1
	v_mul_f32_e32 v64, 0xbfb8aa3b, v56
	v_mul_f32_e32 v65, 0xbfb8aa3b, v57
	v_exp_f32_e32 v64, v64
	v_exp_f32_e32 v65, v65
	s_nop 0
	v_pk_add_f32 v[64:65], v[64:65], 1.0 op_sel_hi:[1,0]
	s_nop 0
	v_rcp_f32_e32 v66, v65
	s_nop 0
	v_mul_f32_e32 v57, v57, v66
	v_rcp_f32_e32 v65, v64
	s_nop 0
	v_mul_f32_e32 v56, v56, v65
	v_pk_mul_f32 v[56:57], v[56:57], v[60:61]
	v_mul_f32_e32 v60, 0xbfb8aa3b, v58
	v_mul_f32_e32 v61, 0xbfb8aa3b, v59
	v_exp_f32_e32 v60, v60
	v_exp_f32_e32 v61, v61
	v_cvt_pk_bf16_f32 v56, v56, v57
	v_pk_add_f32 v[60:61], v[60:61], 1.0 op_sel_hi:[1,0]
	s_nop 0
	v_rcp_f32_e32 v64, v61
	s_nop 0
	v_mul_f32_e32 v59, v59, v64
	v_rcp_f32_e32 v61, v60
	s_nop 0
	v_mul_f32_e32 v58, v58, v61
	v_pk_mul_f32 v[58:59], v[58:59], v[62:63]
	s_nop 0
	v_cvt_pk_bf16_f32 v57, v58, v59
	v_mul_f32_e32 v58, 0xbfb8aa3b, v48
	v_mul_f32_e32 v59, 0xbfb8aa3b, v49
	v_exp_f32_e32 v58, v58
	v_exp_f32_e32 v59, v59
	s_nop 0
	v_pk_add_f32 v[58:59], v[58:59], 1.0 op_sel_hi:[1,0]
	s_nop 0
	v_rcp_f32_e32 v60, v59
	s_nop 0
	v_mul_f32_e32 v49, v49, v60
	v_rcp_f32_e32 v59, v58
	s_nop 0
	v_mul_f32_e32 v48, v48, v59
	v_pk_mul_f32 v[48:49], v[48:49], v[52:53]
	v_mul_f32_e32 v52, 0xbfb8aa3b, v50
	v_mul_f32_e32 v53, 0xbfb8aa3b, v51
	v_exp_f32_e32 v52, v52
	v_exp_f32_e32 v53, v53
	s_nop 0
	v_pk_add_f32 v[52:53], v[52:53], 1.0 op_sel_hi:[1,0]
	s_nop 0
	v_rcp_f32_e32 v58, v53
	s_nop 0
	v_mul_f32_e32 v51, v51, v58
	v_cvt_pk_bf16_f32 v58, v48, v49
	v_add_u32_e32 v48, 0x80, v114
	v_mad_i64_i32 v[48:49], s[24:25], v48, s29, v[112:113]
	v_rcp_f32_e32 v53, v52
	s_nop 0
	v_mul_f32_e32 v50, v50, v53
	v_lshl_add_u64 v[48:49], v[48:49], 0, s[4:5]
	v_pk_mul_f32 v[50:51], v[50:51], v[54:55]
	v_lshl_add_u64 v[48:49], v[48:49], 0, s[84:85]
	v_cvt_pk_bf16_f32 v59, v50, v51
	v_lshl_add_u64 v[48:49], v[48:49], 0, v[144:145]
	global_store_dwordx4 v[48:49], v[56:59], off sc1
	v_mul_f32_e32 v48, 0xbfb8aa3b, v40
	v_mul_f32_e32 v49, 0xbfb8aa3b, v41
	v_exp_f32_e32 v48, v48
	v_exp_f32_e32 v49, v49
	s_nop 0
	v_pk_add_f32 v[48:49], v[48:49], 1.0 op_sel_hi:[1,0]
	s_nop 0
	v_rcp_f32_e32 v50, v49
	s_nop 0
	v_mul_f32_e32 v41, v41, v50
	v_rcp_f32_e32 v49, v48
	s_nop 0
	v_mul_f32_e32 v40, v40, v49
	v_pk_mul_f32 v[40:41], v[40:41], v[44:45]
	v_mul_f32_e32 v44, 0xbfb8aa3b, v42
	v_mul_f32_e32 v45, 0xbfb8aa3b, v43
	v_exp_f32_e32 v44, v44
	v_exp_f32_e32 v45, v45
	v_cvt_pk_bf16_f32 v40, v40, v41
	v_pk_add_f32 v[44:45], v[44:45], 1.0 op_sel_hi:[1,0]
	s_nop 0
	v_rcp_f32_e32 v48, v45
	s_nop 0
	v_mul_f32_e32 v43, v43, v48
	v_rcp_f32_e32 v45, v44
	s_nop 0
	v_mul_f32_e32 v42, v42, v45
	v_pk_mul_f32 v[42:43], v[42:43], v[46:47]
	s_nop 0
	v_cvt_pk_bf16_f32 v41, v42, v43
	v_mul_f32_e32 v42, 0xbfb8aa3b, v32
	v_mul_f32_e32 v43, 0xbfb8aa3b, v33
	v_exp_f32_e32 v42, v42
	v_exp_f32_e32 v43, v43
	s_nop 0
	v_pk_add_f32 v[42:43], v[42:43], 1.0 op_sel_hi:[1,0]
	s_nop 0
	v_rcp_f32_e32 v44, v43
	s_nop 0
	v_mul_f32_e32 v33, v33, v44
	v_rcp_f32_e32 v43, v42
	s_nop 0
	v_mul_f32_e32 v32, v32, v43
	v_pk_mul_f32 v[32:33], v[32:33], v[36:37]
	v_mul_f32_e32 v36, 0xbfb8aa3b, v34
	v_mul_f32_e32 v37, 0xbfb8aa3b, v35
	v_exp_f32_e32 v36, v36
	v_exp_f32_e32 v37, v37
	s_nop 0
	v_pk_add_f32 v[36:37], v[36:37], 1.0 op_sel_hi:[1,0]
	s_nop 0
	v_rcp_f32_e32 v42, v37
	s_nop 0
	v_mul_f32_e32 v35, v35, v42
	v_cvt_pk_bf16_f32 v42, v32, v33
	v_add_u32_e32 v32, 0x90, v114
	v_mad_i64_i32 v[32:33], s[24:25], v32, s29, v[112:113]
	v_rcp_f32_e32 v37, v36
	s_nop 0
	v_mul_f32_e32 v34, v34, v37
	v_lshl_add_u64 v[32:33], v[32:33], 0, s[4:5]
	v_pk_mul_f32 v[34:35], v[34:35], v[38:39]
	v_lshl_add_u64 v[32:33], v[32:33], 0, s[84:85]
	v_cvt_pk_bf16_f32 v43, v34, v35
	v_lshl_add_u64 v[32:33], v[32:33], 0, v[144:145]
	global_store_dwordx4 v[32:33], v[40:43], off sc1
	v_mul_f32_e32 v32, 0xbfb8aa3b, v24
	v_mul_f32_e32 v33, 0xbfb8aa3b, v25
	v_exp_f32_e32 v32, v32
	v_exp_f32_e32 v33, v33
	s_nop 0
	v_pk_add_f32 v[32:33], v[32:33], 1.0 op_sel_hi:[1,0]
	s_nop 0
	v_rcp_f32_e32 v34, v33
	s_nop 0
	v_mul_f32_e32 v25, v25, v34
	v_rcp_f32_e32 v33, v32
	s_nop 0
	v_mul_f32_e32 v24, v24, v33
	v_pk_mul_f32 v[24:25], v[24:25], v[28:29]
	v_mul_f32_e32 v28, 0xbfb8aa3b, v26
	v_mul_f32_e32 v29, 0xbfb8aa3b, v27
	v_exp_f32_e32 v28, v28
	v_exp_f32_e32 v29, v29
	v_cvt_pk_bf16_f32 v24, v24, v25
	v_pk_add_f32 v[28:29], v[28:29], 1.0 op_sel_hi:[1,0]
	s_nop 0
	v_rcp_f32_e32 v32, v29
	s_nop 0
	v_mul_f32_e32 v27, v27, v32
	v_rcp_f32_e32 v29, v28
	s_nop 0
	v_mul_f32_e32 v26, v26, v29
	v_pk_mul_f32 v[26:27], v[26:27], v[30:31]
	s_nop 0
	v_cvt_pk_bf16_f32 v25, v26, v27
	v_mul_f32_e32 v26, 0xbfb8aa3b, v16
	v_mul_f32_e32 v27, 0xbfb8aa3b, v17
	v_exp_f32_e32 v26, v26
	v_exp_f32_e32 v27, v27
	s_nop 0
	v_pk_add_f32 v[26:27], v[26:27], 1.0 op_sel_hi:[1,0]
	s_nop 0
	v_rcp_f32_e32 v28, v27
	s_nop 0
	v_mul_f32_e32 v17, v17, v28
	v_rcp_f32_e32 v27, v26
	s_nop 0
	v_mul_f32_e32 v16, v16, v27
	v_pk_mul_f32 v[16:17], v[16:17], v[20:21]
	v_mul_f32_e32 v20, 0xbfb8aa3b, v18
	v_mul_f32_e32 v21, 0xbfb8aa3b, v19
	v_exp_f32_e32 v20, v20
	v_exp_f32_e32 v21, v21
	s_nop 0
	v_pk_add_f32 v[20:21], v[20:21], 1.0 op_sel_hi:[1,0]
	s_nop 0
	v_rcp_f32_e32 v26, v21
	s_nop 0
	v_mul_f32_e32 v19, v19, v26
	v_cvt_pk_bf16_f32 v26, v16, v17
	v_add_u32_e32 v16, 0xa0, v114
	v_mad_i64_i32 v[16:17], s[24:25], v16, s29, v[112:113]
	v_rcp_f32_e32 v21, v20
	s_nop 0
	v_mul_f32_e32 v18, v18, v21
	v_lshl_add_u64 v[16:17], v[16:17], 0, s[4:5]
	v_pk_mul_f32 v[18:19], v[18:19], v[22:23]
	v_lshl_add_u64 v[16:17], v[16:17], 0, s[84:85]
	v_cvt_pk_bf16_f32 v27, v18, v19
	v_lshl_add_u64 v[16:17], v[16:17], 0, v[144:145]
	global_store_dwordx4 v[16:17], v[24:27], off sc1
	v_mul_f32_e32 v16, 0xbfb8aa3b, v8
	v_mul_f32_e32 v17, 0xbfb8aa3b, v9
	v_exp_f32_e32 v16, v16
	v_exp_f32_e32 v17, v17
	s_nop 0
	v_pk_add_f32 v[16:17], v[16:17], 1.0 op_sel_hi:[1,0]
	s_nop 0
	v_rcp_f32_e32 v18, v17
	s_nop 0
	v_mul_f32_e32 v9, v9, v18
	v_rcp_f32_e32 v17, v16
	s_nop 0
	v_mul_f32_e32 v8, v8, v17
	v_pk_mul_f32 v[8:9], v[8:9], v[12:13]
	v_mul_f32_e32 v12, 0xbfb8aa3b, v10
	v_mul_f32_e32 v13, 0xbfb8aa3b, v11
	v_exp_f32_e32 v12, v12
	v_exp_f32_e32 v13, v13
	v_cvt_pk_bf16_f32 v8, v8, v9
	v_pk_add_f32 v[12:13], v[12:13], 1.0 op_sel_hi:[1,0]
	s_nop 0
	v_rcp_f32_e32 v16, v13
	s_nop 0
	v_mul_f32_e32 v11, v11, v16
	v_rcp_f32_e32 v13, v12
	s_nop 0
	v_mul_f32_e32 v10, v10, v13
	v_pk_mul_f32 v[10:11], v[10:11], v[14:15]
	s_nop 0
	v_cvt_pk_bf16_f32 v9, v10, v11
	v_mul_f32_e32 v10, 0xbfb8aa3b, v0
	v_mul_f32_e32 v11, 0xbfb8aa3b, v1
	v_exp_f32_e32 v10, v10
	v_exp_f32_e32 v11, v11
	s_nop 0
	v_pk_add_f32 v[10:11], v[10:11], 1.0 op_sel_hi:[1,0]
	s_nop 0
	v_rcp_f32_e32 v12, v11
	s_nop 0
	v_mul_f32_e32 v1, v1, v12
	v_rcp_f32_e32 v11, v10
	s_nop 0
	v_mul_f32_e32 v0, v0, v11
	v_pk_mul_f32 v[0:1], v[0:1], v[4:5]
	v_mul_f32_e32 v4, 0xbfb8aa3b, v2
	v_mul_f32_e32 v5, 0xbfb8aa3b, v3
	v_exp_f32_e32 v4, v4
	v_exp_f32_e32 v5, v5
	s_nop 0
	v_pk_add_f32 v[4:5], v[4:5], 1.0 op_sel_hi:[1,0]
	s_nop 0
	v_rcp_f32_e32 v10, v5
	s_nop 0
	v_mul_f32_e32 v3, v3, v10
	v_cvt_pk_bf16_f32 v10, v0, v1
	v_add_u32_e32 v0, 0xb0, v114
	v_mad_i64_i32 v[0:1], s[24:25], v0, s29, v[112:113]
	v_rcp_f32_e32 v5, v4
	s_nop 0
	v_mul_f32_e32 v2, v2, v5
	v_lshl_add_u64 v[0:1], v[0:1], 0, s[4:5]
	v_pk_mul_f32 v[2:3], v[2:3], v[6:7]
	v_lshl_add_u64 v[0:1], v[0:1], 0, s[84:85]
	v_cvt_pk_bf16_f32 v11, v2, v3
	v_lshl_add_u64 v[0:1], v[0:1], 0, v[144:145]
	global_store_dwordx4 v[0:1], v[8:11], off sc1
	s_load_dword s4, s[80:81], 0x0
	s_load_dword s5, s[80:81], 0x10
	s_waitcnt lgkmcnt(0)
	s_lshr_b32 s5, s5, 16
	s_cmp_lg_u32 s5, 0
	s_cselect_b64 s[24:25], -1, 0
	s_cmp_lg_u64 s[24:25], 0
	s_addc_u32 s30, s4, s30
	s_cmpk_gt_i32 s30, 0x2bf
	s_cbranch_scc1 .LBB0_798

.LBB0_1515:
	s_or_b64 exec, exec, s[4:5]
	v_cvt_f32_u32_e32 v4, v2
	s_waitcnt vmcnt(0)
	v_readfirstlane_b32 s4, v3
	v_sub_u32_e32 v3, 0, v2
	v_rcp_iflag_f32_e32 v4, v4
	v_add_u32_e32 v5, s4, v1
	v_mul_f32_e32 v4, 0x4f7ffffe, v4
	v_cvt_u32_f32_e32 v4, v4
	v_mul_lo_u32 v1, v3, v4
	v_mul_hi_u32 v1, v4, v1
	v_add_u32_e32 v1, v4, v1
	v_mul_hi_u32 v1, v5, v1
	v_mul_lo_u32 v3, v1, v2
	v_sub_u32_e32 v3, v5, v3
	v_add_u32_e32 v4, 1, v1
	v_cmp_ge_u32_e32 vcc, v3, v2
	s_nop 1
	v_cndmask_b32_e32 v1, v1, v4, vcc
	v_sub_u32_e32 v4, v3, v2
	v_cndmask_b32_e32 v3, v3, v4, vcc
	v_add_u32_e32 v4, 1, v1
	v_cmp_ge_u32_e32 vcc, v3, v2
	v_add_u32_e32 v3, 1, v5
	s_nop 0
	v_cndmask_b32_e32 v1, v1, v4, vcc
	v_mul_lo_u32 v4, v2, v1
	v_add_u32_e32 v2, v4, v2
	v_cmp_ne_u32_e32 vcc, v3, v2
	s_waitcnt lgkmcnt(0)
	v_add_u32_e32 v6, 1, v1
	v_mul_lo_u32 v6, v6, v0
	s_cbranch_vccnz .Lnb_poll
	s_mov_b32 s28, 0x1081080
	s_lshr_b32 s28, s28, s54
	s_bitcmp1_b32 s28, 0
	s_cbranch_scc1 .Lnb_nowb
	buffer_wbl2 sc1
	s_waitcnt vmcnt(0)
.Lnb_nowb:
	s_add_u32 s28, s52, 0x2400
	s_addc_u32 s29, s53, 0
	global_atomic_add v145, v161, s[28:29]
	global_atomic_add v145, v161, s[28:29] offset:256
	global_atomic_add v145, v161, s[28:29] offset:512
	global_atomic_add v145, v161, s[28:29] offset:768
	global_atomic_add v145, v161, s[28:29] offset:1024
	global_atomic_add v145, v161, s[28:29] offset:1280
	global_atomic_add v145, v161, s[28:29] offset:1536
	global_atomic_add v145, v161, s[28:29] offset:1792
	global_atomic_add v145, v161, s[28:29] offset:2048
	global_atomic_add v145, v161, s[28:29] offset:2304
	global_atomic_add v145, v161, s[28:29] offset:2560
	global_atomic_add v145, v161, s[28:29] offset:2816
	global_atomic_add v145, v161, s[28:29] offset:3072
	global_atomic_add v145, v161, s[28:29] offset:3328
	global_atomic_add v145, v161, s[28:29] offset:3584
	global_atomic_add v145, v161, s[28:29] offset:3840
